# v12: v11 + SwiGLU epilogue VALU work reduction (saddr-form stores replace 8 v_mad_i64 per unit; -log2e folded into the row-scale table; op_sel instead of v_mov/v_mul for odd rows)
# speedup vs baseline: 1.0006x; 1.0006x over previous
.LBB0_922:
	s_or_b64 exec, exec, s[74:75]
	v_mov_b32_e32 v1, v0
	s_barrier
	s_lshl_b32 s2, s19, 14
	v_ashrrev_i32_e32 v4, 1, v1
	s_waitcnt vmcnt(26)
	v_ashrrev_i32_e32 v5, 31, v4
	s_add_u32 s2, s20, s2
	s_waitcnt vmcnt(24)
	v_and_b32_e32 v7, 1, v1
	s_addc_u32 s3, s36, 0
	s_waitcnt vmcnt(22)
	v_lshlrev_b64 v[8:9], 6, v[4:5]
	v_lshl_add_u64 v[8:9], s[2:3], 0, v[8:9]
	v_lshlrev_b32_e32 v2, 5, v7
	s_waitcnt vmcnt(14)
	v_lshl_add_u64 v[16:17], v[8:9], 0, v[2:3]
	global_load_dwordx4 v[8:11], v[16:17], off sc1
	global_load_dwordx4 v[12:15], v[16:17], off offset:16 sc1
	s_waitcnt vmcnt(0)
	s_nop 0
	v_add_f32_e32 v1, v8, v9
	v_add_f32_e32 v2, v10, v11
	v_add_f32_e32 v1, v1, v2
	v_add_f32_e32 v2, v12, v13
	v_add_f32_e32 v5, v14, v15
	v_add_f32_e32 v2, v2, v5
	v_and_b32_e32 v5, 64, v192
	v_add_f32_e32 v1, v1, v2
	v_xor_b32_e32 v2, 1, v192
	v_add_u32_e32 v5, 64, v5
	v_cmp_lt_i32_e32 vcc, v2, v5
	s_nop 1
	v_cndmask_b32_e32 v2, v192, v2, vcc
	v_lshlrev_b32_e32 v2, 2, v2
	ds_bpermute_b32 v2, v2, v1
	v_cmp_eq_u32_e32 vcc, 0, v7
	s_and_saveexec_b64 s[2:3], vcc
	s_cbranch_execz .LBB0_924
	s_waitcnt lgkmcnt(0)
	v_add_f32_e32 v1, v1, v2
	v_fmamk_f32 v1, v1, 0x3a800000, v254
	s_lshl_b32 s8, s19, 8
	v_rsq_f32_e32 v2, v1
	s_and_b32 s8, s8, 0x400
	s_add_i32 s8, s8, 0
	v_lshl_add_u32 v4, v4, 2, s8
	v_add_u32_e32 v4, 0x24400, v4
	v_mul_f32_e32 v2, 0xbfb8aa3b, v2
	ds_write2st64_b32 v4, v2, v1 offset1:8

.LBB0_1042:
	v_mov_b32_e32 v2, v0
	s_lshl_b32 s2, s19, 14
	v_ashrrev_i32_e32 v4, 1, v2
	v_ashrrev_i32_e32 v5, 31, v4
	s_add_u32 s2, s20, s2
	v_and_b32_e32 v11, 1, v2
	s_addc_u32 s3, s36, 0
	s_waitcnt vmcnt(18)
	v_lshlrev_b64 v[12:13], 6, v[4:5]
	v_lshl_add_u64 v[12:13], s[2:3], 0, v[12:13]
	v_lshlrev_b32_e32 v2, 5, v11
	s_waitcnt vmcnt(10)
	v_lshl_add_u64 v[20:21], v[12:13], 0, v[2:3]
	global_load_dwordx4 v[12:15], v[20:21], off sc1
	global_load_dwordx4 v[16:19], v[20:21], off offset:16 sc1
	s_waitcnt lgkmcnt(0)
	s_add_u32 s51, s70, 0x2a00000
	s_addc_u32 s97, s71, 0
	s_lshl_b32 s2, s19, 19
	s_add_u32 s62, s51, s2
	s_addc_u32 s63, s97, 0
	v_lshl_add_u32 v147, v7, 11, v8
	s_add_i32 m0, s69, 0
	s_nop 0
	global_load_lds_dwordx4 v147, s[62:63]
	s_ashr_i32 s2, s14, 8
	v_lshl_add_u32 v148, v9, 11, v10
	s_add_i32 m0, s69, 0x2000
	s_nop 0
	global_load_lds_dwordx4 v148, s[62:63]
	s_add_u32 s12, s62, 0x40000
	s_addc_u32 s13, s63, 0
	s_add_i32 m0, s69, 0x4000
	s_nop 0
	global_load_lds_dwordx4 v147, s[12:13]
	s_nop 0
	s_add_i32 m0, s69, 0x6000
	s_nop 0
	global_load_lds_dwordx4 v148, s[12:13]
	s_waitcnt vmcnt(4)
	s_nop 0
	v_add_f32_e32 v2, v12, v13
	v_add_f32_e32 v5, v14, v15
	v_add_f32_e32 v2, v2, v5
	v_add_f32_e32 v5, v16, v17
	v_add_f32_e32 v12, v18, v19
	v_add_f32_e32 v5, v5, v12
	v_and_b32_e32 v12, 64, v192
	v_add_f32_e32 v2, v2, v5
	v_xor_b32_e32 v5, 1, v192
	v_add_u32_e32 v12, 64, v12
	v_cmp_lt_i32_e32 vcc, v5, v12
	s_nop 1
	v_cndmask_b32_e32 v5, v192, v5, vcc
	v_lshlrev_b32_e32 v5, 2, v5
	ds_bpermute_b32 v5, v5, v2
	v_cmp_eq_u32_e32 vcc, 0, v11
	s_and_saveexec_b64 s[2:3], vcc
	s_cbranch_execz .LBB0_1044
	s_waitcnt lgkmcnt(0)
	v_add_f32_e32 v2, v2, v5
	v_fmamk_f32 v2, v2, 0x3a800000, v254
	s_lshl_b32 s7, s19, 8
	v_rsq_f32_e32 v5, v2
	s_and_b32 s7, s7, 0x400
	s_add_i32 s7, s7, 0
	v_lshl_add_u32 v4, v4, 2, s7
	v_add_u32_e32 v4, 0x24400, v4
	v_mul_f32_e32 v5, 0xbfb8aa3b, v5
	ds_write2st64_b32 v4, v5, v2 offset1:8

.LBB0_1189:
	v_mov_b32_e32 v2, v0
	s_nop 0
	v_ashrrev_i32_e32 v132, 1, v2
	v_ashrrev_i32_e32 v133, 31, v132
	v_and_b32_e32 v153, 1, v2
	v_lshlrev_b64 v[138:139], 6, v[132:133]
	v_lshl_add_u64 v[138:139], s[84:85], 0, v[138:139]
	v_lshlrev_b32_e32 v2, 5, v153
	v_lshl_add_u64 v[154:155], v[138:139], 0, v[2:3]
	global_load_dwordx4 v[138:141], v[154:155], off sc1
	global_load_dwordx4 v[142:145], v[154:155], off offset:16 sc1
	s_waitcnt vmcnt(0)
	s_nop 0
	v_add_f32_e32 v2, v138, v139
	v_add_f32_e32 v133, v140, v141
	v_add_f32_e32 v2, v2, v133
	v_add_f32_e32 v133, v142, v143
	v_add_f32_e32 v138, v144, v145
	v_add_f32_e32 v133, v133, v138
	v_and_b32_e32 v138, 64, v192
	v_add_f32_e32 v2, v2, v133
	v_xor_b32_e32 v133, 1, v192
	v_add_u32_e32 v138, 64, v138
	v_cmp_lt_i32_e32 vcc, v133, v138
	s_nop 1
	v_cndmask_b32_e32 v133, v192, v133, vcc
	v_lshlrev_b32_e32 v133, 2, v133
	ds_bpermute_b32 v133, v133, v2
	v_cmp_eq_u32_e32 vcc, 0, v153
	s_and_saveexec_b64 s[2:3], vcc
	s_cbranch_execz .LBB0_1191
	s_waitcnt lgkmcnt(0)
	v_add_f32_e32 v2, v2, v133
	v_fmamk_f32 v2, v2, 0x3a800000, v254
	v_rsq_f32_e32 v133, v2
	v_lshl_add_u32 v132, v132, 2, s83
	v_mul_f32_e32 v133, 0xbfb8aa3b, v133
	ds_write2st64_b32 v132, v133, v2 offset1:8

.LBB0_1198:
	s_lshl_b32 s6, s45, 8
	s_and_b32 s6, s6, 0x400
	v_mov_b32_e32 v2, v150
	v_mov_b32_e32 v133, v149
	s_add_i32 s6, s55, s6
	v_pk_mul_f32 v[130:131], v[126:127], v[130:131]
	v_lshl_add_u32 v132, v133, 2, s6
	ds_read2_b32 v[154:155], v132 offset1:16
	v_add_u32_e32 v134, 0x800, v132
	ds_read2_b32 v[156:157], v134 offset1:16
	ds_read2_b32 v[144:145], v132 offset0:32 offset1:48
	ds_read2_b32 v[142:143], v134 offset0:32 offset1:48
	ds_read2_b32 v[140:141], v132 offset0:128 offset1:144
	ds_read2_b32 v[138:139], v134 offset0:128 offset1:144
	ds_read2_b32 v[136:137], v132 offset0:160 offset1:176
	ds_read2_b32 v[134:135], v134 offset0:160 offset1:176
	s_lshl_b32 s6, s68, 7
	s_mul_i32 s2, s45, 0x1a0000
	s_waitcnt lgkmcnt(7)
	v_pk_mul_f32 v[158:159], v[124:125], v[154:155] op_sel_hi:[1,0]
	v_pk_mul_f32 v[124:125], v[124:125], v[128:129]
	v_pk_mul_f32 v[128:129], v[116:117], v[154:155] op_sel_hi:[1,0]
	v_pk_mul_f32 v[116:117], v[116:117], v[120:121]
	v_exp_f32_e32 v128, v128
	v_exp_f32_e32 v129, v129
	v_exp_f32_e32 v158, v158
	v_exp_f32_e32 v159, v159
	v_pk_mul_f32 v[126:127], v[126:127], v[154:155] op_sel_hi:[1,0]
	s_waitcnt lgkmcnt(6)
	v_pk_fma_f32 v[128:129], v[156:157], v[128:129], v[156:157] op_sel_hi:[0,1,0]
	v_rcp_f32_e32 v128, v128
	v_rcp_f32_e32 v129, v129
	v_exp_f32_e32 v126, v126
	v_exp_f32_e32 v127, v127
	v_pk_fma_f32 v[158:159], v[156:157], v[158:159], v[156:157] op_sel_hi:[0,1,0]
	v_pk_mul_f32 v[120:121], v[116:117], v[128:129]
	v_pk_mul_f32 v[116:117], v[118:119], v[154:155] op_sel_hi:[1,0]
	v_rcp_f32_e32 v158, v158
	v_exp_f32_e32 v116, v116
	v_exp_f32_e32 v117, v117
	v_rcp_f32_e32 v159, v159
	v_pk_fma_f32 v[126:127], v[156:157], v[126:127], v[156:157] op_sel_hi:[0,1,0]
	v_rcp_f32_e32 v126, v126
	v_pk_fma_f32 v[116:117], v[156:157], v[116:117], v[156:157] op_sel_hi:[0,1,0]
	v_rcp_f32_e32 v127, v127
	v_rcp_f32_e32 v116, v116
	v_rcp_f32_e32 v117, v117
	s_or_b32 s6, s6, s44
	s_mul_hi_i32 s3, s45, 0x1a0000
	v_lshl_add_u32 v132, v2, 3, s6
	s_add_u32 s2, s98, s2
	s_addc_u32 s3, s99, s3
	v_add_u32_e32 v2, s61, v133
	v_mul_u32_u24_e32 v133, 0x1600, v2
	v_pk_mul_f32 v[124:125], v[124:125], v[158:159]
	v_pk_mul_f32 v[122:123], v[118:119], v[122:123]
	v_lshl_add_u32 v132, v132, 1, v133
	v_pk_mul_f32 v[126:127], v[130:131], v[126:127]
	v_pk_mul_f32 v[122:123], v[122:123], v[116:117]
	v_cvt_pk_bf16_f32 v116, v124, v125
	v_cvt_pk_bf16_f32 v117, v126, v127
	v_cvt_pk_bf16_f32 v118, v120, v121
	v_cvt_pk_bf16_f32 v119, v122, v123
	global_store_dwordx4 v132, v[116:119], s[2:3] sc1
	s_nop 1
	v_pk_mul_f32 v[120:121], v[108:109], v[154:155] op_sel:[0,1] op_sel_hi:[1,1]
	v_pk_mul_f32 v[108:109], v[108:109], v[112:113]
	v_pk_mul_f32 v[112:113], v[100:101], v[154:155] op_sel:[0,1] op_sel_hi:[1,1]
	v_exp_f32_e32 v112, v112
	v_exp_f32_e32 v113, v113
	v_pk_mul_f32 v[100:101], v[100:101], v[104:105]
	v_exp_f32_e32 v120, v120
	v_exp_f32_e32 v121, v121
	v_pk_fma_f32 v[112:113], v[156:157], v[112:113], v[156:157] op_sel:[1,0,1] op_sel_hi:[1,1,1]
	v_rcp_f32_e32 v112, v112
	v_rcp_f32_e32 v113, v113
	v_pk_mul_f32 v[114:115], v[110:111], v[114:115]
	v_pk_mul_f32 v[110:111], v[110:111], v[154:155] op_sel:[0,1] op_sel_hi:[1,1]
	v_pk_fma_f32 v[120:121], v[156:157], v[120:121], v[156:157] op_sel:[1,0,1] op_sel_hi:[1,1,1]
	v_pk_mul_f32 v[104:105], v[100:101], v[112:113]
	v_pk_mul_f32 v[100:101], v[102:103], v[154:155] op_sel:[0,1] op_sel_hi:[1,1]
	v_exp_f32_e32 v110, v110
	v_exp_f32_e32 v111, v111
	v_exp_f32_e32 v100, v100
	v_exp_f32_e32 v101, v101
	v_rcp_f32_e32 v120, v120
	v_rcp_f32_e32 v121, v121
	v_pk_fma_f32 v[110:111], v[156:157], v[110:111], v[156:157] op_sel:[1,0,1] op_sel_hi:[1,1,1]
	v_pk_fma_f32 v[100:101], v[156:157], v[100:101], v[156:157] op_sel:[1,0,1] op_sel_hi:[1,1,1]
	v_rcp_f32_e32 v110, v110
	v_rcp_f32_e32 v111, v111
	v_rcp_f32_e32 v100, v100
	v_rcp_f32_e32 v101, v101
	v_pk_mul_f32 v[108:109], v[108:109], v[120:121]
	v_pk_mul_f32 v[106:107], v[102:103], v[106:107]
	v_pk_mul_f32 v[110:111], v[114:115], v[110:111]
	v_pk_mul_f32 v[106:107], v[106:107], v[100:101]
	v_add_u32_e32 v112, 0x16000, v132
	v_cvt_pk_bf16_f32 v100, v108, v109
	v_cvt_pk_bf16_f32 v101, v110, v111
	v_cvt_pk_bf16_f32 v102, v104, v105
	v_cvt_pk_bf16_f32 v103, v106, v107
	global_store_dwordx4 v112, v[100:103], s[2:3] sc1
	s_nop 1
	s_waitcnt lgkmcnt(5)
	v_pk_mul_f32 v[102:103], v[92:93], v[144:145] op_sel_hi:[1,0]
	v_pk_mul_f32 v[92:93], v[92:93], v[96:97]
	v_pk_mul_f32 v[96:97], v[84:85], v[144:145] op_sel_hi:[1,0]
	v_pk_mul_f32 v[84:85], v[84:85], v[88:89]
	v_exp_f32_e32 v96, v96
	v_exp_f32_e32 v97, v97
	v_exp_f32_e32 v102, v102
	v_exp_f32_e32 v103, v103
	v_pk_mul_f32 v[98:99], v[94:95], v[98:99]
	s_waitcnt lgkmcnt(4)
	v_pk_fma_f32 v[96:97], v[142:143], v[96:97], v[142:143] op_sel_hi:[0,1,0]
	v_rcp_f32_e32 v96, v96
	v_rcp_f32_e32 v97, v97
	v_pk_mul_f32 v[94:95], v[94:95], v[144:145] op_sel_hi:[1,0]
	v_pk_fma_f32 v[102:103], v[142:143], v[102:103], v[142:143] op_sel_hi:[0,1,0]
	v_exp_f32_e32 v94, v94
	v_pk_mul_f32 v[88:89], v[84:85], v[96:97]
	v_pk_mul_f32 v[84:85], v[86:87], v[144:145] op_sel_hi:[1,0]
	v_exp_f32_e32 v95, v95
	v_exp_f32_e32 v84, v84
	v_exp_f32_e32 v85, v85
	v_rcp_f32_e32 v102, v102
	v_rcp_f32_e32 v103, v103
	v_pk_fma_f32 v[94:95], v[142:143], v[94:95], v[142:143] op_sel_hi:[0,1,0]
	v_pk_fma_f32 v[84:85], v[142:143], v[84:85], v[142:143] op_sel_hi:[0,1,0]
	v_rcp_f32_e32 v94, v94
	v_rcp_f32_e32 v95, v95
	v_rcp_f32_e32 v84, v84
	v_rcp_f32_e32 v85, v85
	v_pk_mul_f32 v[92:93], v[92:93], v[102:103]
	v_pk_mul_f32 v[90:91], v[86:87], v[90:91]
	v_pk_mul_f32 v[94:95], v[98:99], v[94:95]
	v_pk_mul_f32 v[90:91], v[90:91], v[84:85]
	v_add_u32_e32 v96, 0x2c000, v132
	v_cvt_pk_bf16_f32 v84, v92, v93
	v_cvt_pk_bf16_f32 v85, v94, v95
	v_cvt_pk_bf16_f32 v86, v88, v89
	v_cvt_pk_bf16_f32 v87, v90, v91
	global_store_dwordx4 v96, v[84:87], s[2:3] sc1
	s_nop 1
	v_pk_mul_f32 v[88:89], v[76:77], v[144:145] op_sel:[0,1] op_sel_hi:[1,1]
	v_pk_mul_f32 v[76:77], v[76:77], v[80:81]
	v_pk_mul_f32 v[80:81], v[64:65], v[144:145] op_sel:[0,1] op_sel_hi:[1,1]
	v_exp_f32_e32 v80, v80
	v_exp_f32_e32 v81, v81
	v_pk_mul_f32 v[82:83], v[78:79], v[82:83]
	v_pk_mul_f32 v[78:79], v[78:79], v[144:145] op_sel:[0,1] op_sel_hi:[1,1]
	v_pk_mul_f32 v[64:65], v[64:65], v[72:73]
	v_pk_fma_f32 v[80:81], v[142:143], v[80:81], v[142:143] op_sel:[1,0,1] op_sel_hi:[1,1,1]
	v_rcp_f32_e32 v80, v80
	v_rcp_f32_e32 v81, v81
	v_exp_f32_e32 v88, v88
	v_exp_f32_e32 v89, v89
	v_exp_f32_e32 v78, v78
	v_exp_f32_e32 v79, v79
	v_pk_mul_f32 v[72:73], v[64:65], v[80:81]
	v_pk_mul_f32 v[64:65], v[66:67], v[144:145] op_sel:[0,1] op_sel_hi:[1,1]
	v_pk_fma_f32 v[88:89], v[142:143], v[88:89], v[142:143] op_sel:[1,0,1] op_sel_hi:[1,1,1]
	v_exp_f32_e32 v64, v64
	v_exp_f32_e32 v65, v65
	v_pk_fma_f32 v[78:79], v[142:143], v[78:79], v[142:143] op_sel:[1,0,1] op_sel_hi:[1,1,1]
	v_rcp_f32_e32 v88, v88
	v_rcp_f32_e32 v89, v89
	v_rcp_f32_e32 v78, v78
	v_rcp_f32_e32 v79, v79
	v_pk_fma_f32 v[64:65], v[142:143], v[64:65], v[142:143] op_sel:[1,0,1] op_sel_hi:[1,1,1]
	v_rcp_f32_e32 v64, v64
	v_rcp_f32_e32 v65, v65
	v_pk_mul_f32 v[76:77], v[76:77], v[88:89]
	v_pk_mul_f32 v[78:79], v[82:83], v[78:79]
	v_pk_mul_f32 v[74:75], v[66:67], v[74:75]
	v_add_u32_e32 v80, 0x42000, v132
	v_pk_mul_f32 v[74:75], v[74:75], v[64:65]
	v_cvt_pk_bf16_f32 v64, v76, v77
	v_cvt_pk_bf16_f32 v65, v78, v79
	v_cvt_pk_bf16_f32 v66, v72, v73
	v_cvt_pk_bf16_f32 v67, v74, v75
	global_store_dwordx4 v80, v[64:67], s[2:3] sc1
	s_nop 1
	v_add_u32_e32 v65, 0xb0000, v132
	s_waitcnt lgkmcnt(3)
	v_pk_mul_f32 v[66:67], v[60:61], v[140:141] op_sel_hi:[1,0]
	v_pk_mul_f32 v[60:61], v[60:61], v[68:69]
	v_exp_f32_e32 v66, v66
	v_exp_f32_e32 v67, v67
	v_pk_mul_f32 v[70:71], v[62:63], v[70:71]
	v_pk_mul_f32 v[62:63], v[62:63], v[140:141] op_sel_hi:[1,0]
	v_pk_mul_f32 v[58:59], v[54:55], v[58:59]
	s_waitcnt lgkmcnt(2)
	v_pk_fma_f32 v[66:67], v[138:139], v[66:67], v[138:139] op_sel_hi:[0,1,0]
	v_rcp_f32_e32 v66, v66
	v_rcp_f32_e32 v67, v67
	v_exp_f32_e32 v62, v62
	v_exp_f32_e32 v63, v63
	v_pk_mul_f32 v[50:51], v[46:47], v[50:51]
	v_pk_mul_f32 v[60:61], v[60:61], v[66:67]
	v_pk_mul_f32 v[66:67], v[52:53], v[140:141] op_sel_hi:[1,0]
	v_pk_mul_f32 v[52:53], v[52:53], v[56:57]
	v_exp_f32_e32 v66, v66
	v_exp_f32_e32 v67, v67
	v_pk_fma_f32 v[62:63], v[138:139], v[62:63], v[138:139] op_sel_hi:[0,1,0]
	v_rcp_f32_e32 v62, v62
	v_rcp_f32_e32 v63, v63
	v_pk_fma_f32 v[66:67], v[138:139], v[66:67], v[138:139] op_sel_hi:[0,1,0]
	v_rcp_f32_e32 v66, v66
	v_rcp_f32_e32 v67, v67
	v_pk_mul_f32 v[62:63], v[70:71], v[62:63]
	v_pk_mul_f32 v[42:43], v[38:39], v[42:43]
	v_pk_mul_f32 v[34:35], v[30:31], v[34:35]
	v_pk_mul_f32 v[56:57], v[52:53], v[66:67]
	v_pk_mul_f32 v[52:53], v[54:55], v[140:141] op_sel_hi:[1,0]
	v_cvt_pk_bf16_f32 v54, v56, v57
	v_exp_f32_e32 v52, v52
	v_exp_f32_e32 v53, v53
	v_pk_mul_f32 v[26:27], v[22:23], v[26:27]
	v_pk_fma_f32 v[52:53], v[138:139], v[52:53], v[138:139] op_sel_hi:[0,1,0]
	v_rcp_f32_e32 v52, v52
	v_rcp_f32_e32 v53, v53
	v_pk_mul_f32 v[18:19], v[14:15], v[18:19]
	v_pk_mul_f32 v[10:11], v[6:7], v[10:11]
	s_cmp_eq_u32 s82, s45
	v_pk_mul_f32 v[58:59], v[58:59], v[52:53]
	v_cvt_pk_bf16_f32 v52, v60, v61
	v_cvt_pk_bf16_f32 v53, v62, v63
	v_cvt_pk_bf16_f32 v55, v58, v59
	global_store_dwordx4 v65, v[52:55], s[2:3] sc1
	s_nop 1
	v_pk_mul_f32 v[56:57], v[44:45], v[140:141] op_sel:[0,1] op_sel_hi:[1,1]
	v_pk_mul_f32 v[44:45], v[44:45], v[48:49]
	v_pk_mul_f32 v[48:49], v[36:37], v[140:141] op_sel:[0,1] op_sel_hi:[1,1]
	v_exp_f32_e32 v48, v48
	v_exp_f32_e32 v49, v49
	v_pk_mul_f32 v[36:37], v[36:37], v[40:41]
	v_exp_f32_e32 v56, v56
	v_exp_f32_e32 v57, v57
	v_pk_fma_f32 v[48:49], v[138:139], v[48:49], v[138:139] op_sel:[1,0,1] op_sel_hi:[1,1,1]
	v_rcp_f32_e32 v48, v48
	v_rcp_f32_e32 v49, v49
	v_pk_mul_f32 v[46:47], v[46:47], v[140:141] op_sel:[0,1] op_sel_hi:[1,1]
	v_pk_fma_f32 v[56:57], v[138:139], v[56:57], v[138:139] op_sel:[1,0,1] op_sel_hi:[1,1,1]
	v_exp_f32_e32 v46, v46
	v_pk_mul_f32 v[40:41], v[36:37], v[48:49]
	v_pk_mul_f32 v[36:37], v[38:39], v[140:141] op_sel:[0,1] op_sel_hi:[1,1]
	v_exp_f32_e32 v47, v47
	v_exp_f32_e32 v36, v36
	v_exp_f32_e32 v37, v37
	v_rcp_f32_e32 v56, v56
	v_rcp_f32_e32 v57, v57
	v_pk_fma_f32 v[46:47], v[138:139], v[46:47], v[138:139] op_sel:[1,0,1] op_sel_hi:[1,1,1]
	v_pk_fma_f32 v[36:37], v[138:139], v[36:37], v[138:139] op_sel:[1,0,1] op_sel_hi:[1,1,1]
	v_rcp_f32_e32 v46, v46
	v_rcp_f32_e32 v47, v47
	v_rcp_f32_e32 v36, v36
	v_rcp_f32_e32 v37, v37
	v_pk_mul_f32 v[44:45], v[44:45], v[56:57]
	v_pk_mul_f32 v[46:47], v[50:51], v[46:47]
	v_add_u32_e32 v48, 0xc6000, v132
	v_pk_mul_f32 v[42:43], v[42:43], v[36:37]
	v_cvt_pk_bf16_f32 v36, v44, v45
	v_cvt_pk_bf16_f32 v37, v46, v47
	v_cvt_pk_bf16_f32 v38, v40, v41
	v_cvt_pk_bf16_f32 v39, v42, v43
	global_store_dwordx4 v48, v[36:39], s[2:3] sc1
	s_nop 1
	s_waitcnt lgkmcnt(1)
	v_pk_mul_f32 v[38:39], v[28:29], v[136:137] op_sel_hi:[1,0]
	v_pk_mul_f32 v[28:29], v[28:29], v[32:33]
	v_pk_mul_f32 v[32:33], v[20:21], v[136:137] op_sel_hi:[1,0]
	v_pk_mul_f32 v[20:21], v[20:21], v[24:25]
	v_exp_f32_e32 v32, v32
	v_exp_f32_e32 v33, v33
	v_exp_f32_e32 v38, v38
	v_exp_f32_e32 v39, v39
	v_pk_mul_f32 v[30:31], v[30:31], v[136:137] op_sel_hi:[1,0]
	s_waitcnt lgkmcnt(0)
	v_pk_fma_f32 v[32:33], v[134:135], v[32:33], v[134:135] op_sel_hi:[0,1,0]
	v_rcp_f32_e32 v32, v32
	v_rcp_f32_e32 v33, v33
	v_exp_f32_e32 v30, v30
	v_exp_f32_e32 v31, v31
	v_pk_fma_f32 v[38:39], v[134:135], v[38:39], v[134:135] op_sel_hi:[0,1,0]
	v_pk_mul_f32 v[24:25], v[20:21], v[32:33]
	v_pk_mul_f32 v[20:21], v[22:23], v[136:137] op_sel_hi:[1,0]
	v_rcp_f32_e32 v38, v38
	v_exp_f32_e32 v20, v20
	v_exp_f32_e32 v21, v21
	v_rcp_f32_e32 v39, v39
	v_pk_fma_f32 v[30:31], v[134:135], v[30:31], v[134:135] op_sel_hi:[0,1,0]
	v_rcp_f32_e32 v30, v30
	v_pk_fma_f32 v[20:21], v[134:135], v[20:21], v[134:135] op_sel_hi:[0,1,0]
	v_rcp_f32_e32 v31, v31
	v_rcp_f32_e32 v20, v20
	v_rcp_f32_e32 v21, v21
	v_pk_mul_f32 v[28:29], v[28:29], v[38:39]
	v_pk_mul_f32 v[30:31], v[34:35], v[30:31]
	v_add_u32_e32 v32, 0xdc000, v132
	v_pk_mul_f32 v[26:27], v[26:27], v[20:21]
	v_cvt_pk_bf16_f32 v20, v28, v29
	v_cvt_pk_bf16_f32 v21, v30, v31
	v_cvt_pk_bf16_f32 v22, v24, v25
	v_cvt_pk_bf16_f32 v23, v26, v27
	global_store_dwordx4 v32, v[20:23], s[2:3] sc1
	s_nop 1
	v_pk_mul_f32 v[24:25], v[12:13], v[136:137] op_sel:[0,1] op_sel_hi:[1,1]
	v_pk_mul_f32 v[12:13], v[12:13], v[16:17]
	v_pk_mul_f32 v[16:17], v[4:5], v[136:137] op_sel:[0,1] op_sel_hi:[1,1]
	v_exp_f32_e32 v16, v16
	v_exp_f32_e32 v17, v17
	v_pk_mul_f32 v[4:5], v[4:5], v[8:9]
	v_pk_mul_f32 v[14:15], v[14:15], v[136:137] op_sel:[0,1] op_sel_hi:[1,1]
	v_exp_f32_e32 v24, v24
	v_pk_fma_f32 v[16:17], v[134:135], v[16:17], v[134:135] op_sel:[1,0,1] op_sel_hi:[1,1,1]
	v_rcp_f32_e32 v16, v16
	v_rcp_f32_e32 v17, v17
	v_exp_f32_e32 v25, v25
	v_exp_f32_e32 v14, v14
	v_exp_f32_e32 v15, v15
	v_pk_mul_f32 v[8:9], v[4:5], v[16:17]
	v_pk_mul_f32 v[4:5], v[6:7], v[136:137] op_sel:[0,1] op_sel_hi:[1,1]
	v_pk_fma_f32 v[24:25], v[134:135], v[24:25], v[134:135] op_sel:[1,0,1] op_sel_hi:[1,1,1]
	v_exp_f32_e32 v4, v4
	v_exp_f32_e32 v5, v5
	v_pk_fma_f32 v[14:15], v[134:135], v[14:15], v[134:135] op_sel:[1,0,1] op_sel_hi:[1,1,1]
	v_rcp_f32_e32 v24, v24
	v_rcp_f32_e32 v25, v25
	v_pk_fma_f32 v[4:5], v[134:135], v[4:5], v[134:135] op_sel:[1,0,1] op_sel_hi:[1,1,1]
	v_rcp_f32_e32 v14, v14
	v_rcp_f32_e32 v15, v15
	v_rcp_f32_e32 v4, v4
	v_rcp_f32_e32 v5, v5
	v_add_u32_e32 v2, 0xf2000, v132
	v_pk_mul_f32 v[12:13], v[12:13], v[24:25]
	v_pk_mul_f32 v[14:15], v[18:19], v[14:15]
	v_pk_mul_f32 v[10:11], v[10:11], v[4:5]
	v_cvt_pk_bf16_f32 v6, v8, v9
	v_cvt_pk_bf16_f32 v4, v12, v13
	v_cvt_pk_bf16_f32 v5, v14, v15
	v_cvt_pk_bf16_f32 v7, v10, v11
	global_store_dwordx4 v2, v[4:7], s[2:3] sc1
	s_nop 1
	s_cselect_b64 s[2:3], -1, 0
	s_and_b64 s[6:7], s[78:79], s[2:3]
	s_mov_b64 s[2:3], -1
	s_andn2_b64 vcc, exec, s[6:7]
	s_cbranch_vccz .LBB0_1206
	s_waitcnt vmcnt(0)
	s_mov_b64 s[2:3], exec
	v_readlane_b32 s6, v255, 11
	v_readlane_b32 s7, v255, 12
	s_and_b64 s[6:7], s[2:3], s[6:7]
	s_mov_b64 exec, s[6:7]
	s_cbranch_execz .LBB0_1201
	s_lshl_b32 s6, s45, 6
	s_add_i32 s6, s6, s15
	s_ashr_i32 s7, s6, 31
	s_add_i32 s12, s17, 1
	s_lshl_b64 s[6:7], s[6:7], 2
	v_readlane_b32 s13, v255, 5
	s_add_u32 s6, s13, s6
	v_readlane_b32 s13, v255, 6
	s_addc_u32 s7, s13, s7
	v_mov_b32_e32 v2, s12
	global_atomic_add v3, v2, s[6:7]
